# grid barrier: only the 8 XCD leaders poll the global counter; the other workgroups wait on an XCD-local release word the leader bumps
# baseline (speedup 1.0000x reference)
.Lnb_top_done_r:
	v_mov_b32_e32 v6, 1
	global_atomic_add v7, v6, s[10:11] offset:1152
	s_branch .Lnb_done_r
.Lnb_poll_rel_r:
	s_mov_b32 s3, 0
.Lnb_spin_rel_r:
	global_load_dword v6, v7, s[10:11] offset:1152 sc1
	s_waitcnt vmcnt(0)
	v_cmp_le_u32_e32 vcc, v8, v6
	s_cbranch_vccnz .Lnb_done_r
	s_sleep 1
	s_add_i32 s3, s3, 1
	s_cmp_lt_u32 s3, 0x40000
	s_cbranch_scc1 .Lnb_spin_rel_r

.Lnb_poll_rel_m:
	s_mov_b32 s2, 0
.Lnb_spin_rel_m:
	global_load_dword v6, v7, s[10:11] offset:1152 sc1
	s_waitcnt vmcnt(0)
	v_cmp_le_u32_e32 vcc, v8, v6
	s_cbranch_vccnz .Lnb_done_m
	s_sleep 1
	s_add_i32 s2, s2, 1
	s_cmp_lt_u32 s2, 0x40000
	s_cbranch_scc1 .Lnb_spin_rel_m
